# V^T epilogue of the 4th-round GEMM: dwordx2 store pairs merged into dwordx4 via v_permlane32_swap (32 -> 16 stores per lane)
# speedup vs baseline: 1.0011x; 1.0011x over previous
; #define PG8_STAGE(bufoff, gbase) do { _Pragma("unroll") for (int _i = 0; _i < 2; ++_i) \
;         __builtin_amdgcn_global_load_lds((const unsigned*)((const char*)(gbase) + voffA[_i]), (LAS unsigned*)(lds + (bufoff) + ldsw + _i * 8192), 16, 0, 0); } while (0)
; #define PG8_WAIT_V(n) asm volatile("s_waitcnt vmcnt(" #n ")" ::: "memory")
; #define PG8_BAR __builtin_amdgcn_s_barrier()
; template <class Epi, class Sched>
; __device__ __forceinline__ void gemm_phase(LAS unsigned char* lds, const Sched& S, const Epi& E) {
;     ...
;     PG8_STAGE(PG8_SB(0, 0), cB); PG8_STAGE(PG8_SB(0, 1), cB + hstep); PG8_STAGE(PG8_SA(0, 0), cA); PG8_STAGE(PG8_SA(0, 1), cA + hstep);
;     if (wr == 1) PG8_BAR;
;     PG8_WAIT_V(2); PG8_BAR;
;     PG8_STAGE(PG8_SB(1, 0), cB + kstep); PG8_STAGE(PG8_SA(1, 0), cA + kstep); PG8_STAGE(PG8_SB(1, 1), cB + hstep + kstep);
;     PG8_WAIT_V(6); PG8_BAR;
;     __device__ __forceinline__ void operator()(const f32x4 (&acc)[2][2][4][2], const pg8::Unit& u, int wr, int wc, int fr, int fq) const {
;     ...
;             const int sfq = (fq == 1) ? 2 : ((fq == 2) ? 1 : fq);
;             bf16_t* VT = (bf16_t*)(ws + WS_VT);
; #pragma unroll
;             for (int ai = 0; ai < 2; ++ai)
; #pragma unroll
;                 for (int m = 0; m < 4; ++m) {
;                     const int f = 256 * u.pm + 128 * ai + 64 * wr + 16 * m + fr;
;                     bf16_t* rowp = VT + (size_t)f * NTOK + 256 * u.pn + 32 * wc + 4 * sfq;
.LBB0_580:
	s_and_b32 s52, s12, 3
	s_mov_b64 s[12:13], 0x80
	s_add_i32 m0, s48, 0x18000
	v_lshl_add_u64 v[6:7], v[6:7], 0, s[12:13]
	s_lshl_b32 s15, s8, 13
	s_lshl_b32 s53, s52, 5
	s_waitcnt vmcnt(2)
	s_barrier
	global_load_lds_dwordx4 v[6:7], off
	v_lshl_add_u64 v[4:5], v[4:5], 0, s[12:13]
	s_add_i32 m0, s48, 0x1a000
	s_add_i32 s54, s48, 0x8000
	s_add_i32 s55, s48, 0xa000
	global_load_lds_dwordx4 v[4:5], off
	v_lshl_add_u64 v[0:1], v[0:1], 0, s[12:13]
	s_mov_b32 m0, s54
	s_add_u32 s16, s20, 0x80080
	global_load_lds_dwordx4 v[0:1], off
	v_lshl_add_u64 v[0:1], v[2:3], 0, s[12:13]
	s_mov_b32 m0, s55
	s_addc_u32 s17, s21, 0
	global_load_lds_dwordx4 v[0:1], off
	s_add_i32 m0, s48, 0x1c000
	v_lshl_add_u64 v[0:1], s[16:17], 0, v[160:161]
	global_load_lds_dwordx4 v[0:1], off
	v_lshl_add_u64 v[0:1], s[16:17], 0, v[162:163]
	s_add_i32 m0, s48, 0x1e000
	s_cmpk_lt_u32 s14, 0x100
	global_load_lds_dwordx4 v[0:1], off
	v_lshlrev_b32_e32 v1, 2, v226
	v_lshl_or_b32 v0, v226, 6, v227
	v_and_b32_e32 v1, 32, v1
	v_bitop3_b32 v1, v0, s15, v1 bitop3:0xde
	s_cselect_b64 s[14:15], -1, 0
	s_lshl_b32 s56, s8, 4
	s_and_b32 s58, s2, 3
	v_lshlrev_b32_e32 v2, 9, v220
	v_lshl_or_b32 v169, s8, 6, v226
	s_add_i32 s57, s56, 32
	s_lshl_b32 s8, s58, 20
	v_and_b32_e32 v2, 0x70000, v2
	v_lshlrev_b32_e32 v3, 12, v223
	v_lshlrev_b32_e32 v168, 2, v225
	v_cmp_ne_u32_e32 vcc, 2, v225
	s_add_u32 s8, s24, s8
	v_or3_b32 v2, v165, v2, v3
	v_cndmask_b32_e32 v0, 4, v168, vcc
	v_cmp_ne_u32_e32 vcc, 1, v225
	s_addc_u32 s17, s25, 0
	v_add_u32_e32 v172, v2, v222
	v_lshlrev_b32_e32 v2, 5, v224
	s_waitcnt vmcnt(6)
	v_cndmask_b32_e32 v0, 8, v0, vcc
	s_add_u32 s16, s8, 0x1800000
	v_and_b32_e32 v2, 0xf0000, v2
	v_lshl_or_b32 v171, s52, 12, v228
	s_addc_u32 s17, s17, 0
	v_or3_b32 v2, v165, v2, v3
	s_add_i32 s59, 0, 0x10000
	s_add_i32 s60, 0, 0x14000
	v_lshlrev_b32_e32 v176, 1, v0
	v_and_b32_e32 v254, 32, v220
	v_lshrrev_b32_e32 v254, 2, v254
	v_lshl_add_u32 v176, v254, 1, v176
	v_add_u32_e32 v176, v176, v254
	v_mbcnt_lo_u32_b32 v0, -1, 0
	v_or_b32_e32 v190, 16, v169
	v_or_b32_e32 v191, 32, v169
	v_or_b32_e32 v192, 48, v169
	v_add_u32_e32 v193, 0x80, v169
	v_add_u32_e32 v194, 0x90, v169
	v_add_u32_e32 v195, 0xa0, v169
	v_add_u32_e32 v196, 0xb0, v169
	v_lshlrev_b32_e32 v170, 4, v226
	v_mov_b32_e32 v173, v167
	v_add_u32_e32 v174, v2, v222
	v_mov_b32_e32 v175, v167
	v_add_u32_e32 v165, s59, v171
	v_add_u32_e32 v197, s60, v171
	v_add_u32_e32 v198, 0, v1
	s_mov_b64 s[18:19], 0x8c00000
	s_mov_b32 s61, 0x7c00000
	s_movk_i32 s62, 0x4200
	s_mov_b64 s[30:31], 0x10000
	v_mov_b32_e32 v199, 0x358637bd
	s_waitcnt lgkmcnt(0)
	s_mov_b64 s[34:35], 0x1000
	s_mov_b64 s[36:37], 0x1800
	v_mbcnt_hi_u32_b32 v200, -1, v0
	s_mov_b32 s63, 0
	s_mov_b64 s[40:41], s[20:21]
	s_mov_b64 s[42:43], s[4:5]
	s_barrier
	s_branch .LBB0_583

; __device__ __forceinline__ unsigned cvtpk(float lo, float hi) { f32x2 v = {lo, hi}; bf16x2_t b = __builtin_convertvector(v, bf16x2_t); return __builtin_bit_cast(unsigned, b); }
;     __device__ __forceinline__ void operator()(const f32x4 (&acc)[2][2][4][2], const pg8::Unit& u, int wr, int wc, int fr, int fq) const {
;     ...
;             for (int ai = 0; ai < 2; ++ai)
; #pragma unroll
;                 for (int m = 0; m < 4; ++m) {
;                     const int f = 256 * u.pm + 128 * ai + 64 * wr + 16 * m + fr;
;                     bf16_t* rowp = VT + (size_t)f * NTOK + 256 * u.pn + 32 * wc + 4 * sfq;
; #pragma unroll
;                     for (int bj = 0; bj < 2; ++bj)
; #pragma unroll
;                         for (int n = 0; n < 2; ++n) { const f32x4 v = acc[ai][bj][m][n]; u32x2 w; w.x = cvtpk(v[0], v[1]); w.y = cvtpk(v[2], v[3]); *(u32x2*)(rowp + 128 * bj + 16 * n) = w; }
;                 }
.LBB0_611:
	s_add_u32 s4, s44, 0x6b00000
	s_addc_u32 s5, s45, 0
	s_lshl_b32 s28, s67, 8
	v_add_u32_e32 v130, s28, v169
	v_mov_b64_e32 v[128:129], s[4:5]
	v_mad_i64_i32 v[130:131], s[4:5], v130, s62, v[128:129]
	s_lshl_b32 s4, s68, 8
	s_ashr_i32 s5, s4, 31
	s_lshl_b64 s[4:5], s[4:5], 1
	v_lshl_add_u64 v[130:131], v[130:131], 0, s[4:5]
	s_lshl_b32 s8, s53, 1
	v_lshl_add_u64 v[130:131], v[130:131], 0, s[8:9]
	v_mov_b32_e32 v177, v167
	v_lshl_add_u64 v[130:131], v[130:131], 0, v[176:177]
	v_cvt_pk_bf16_f32 v132, v124, v125
	v_cvt_pk_bf16_f32 v133, v126, v127
	v_cvt_pk_bf16_f32 v134, v120, v121
	v_cvt_pk_bf16_f32 v135, v122, v123
	s_nop 1
	v_permlane32_swap_b32_e32 v132, v134
	v_permlane32_swap_b32_e32 v133, v135
	global_store_dwordx4 v[130:131], v[132:135], off
	v_cvt_pk_bf16_f32 v136, v116, v117
	v_cvt_pk_bf16_f32 v137, v118, v119
	v_cvt_pk_bf16_f32 v138, v112, v113
	v_cvt_pk_bf16_f32 v139, v114, v115
	s_nop 1
	v_permlane32_swap_b32_e32 v136, v138
	v_permlane32_swap_b32_e32 v137, v139
	global_store_dwordx4 v[130:131], v[136:139], off offset:256
	v_add_u32_e32 v130, s28, v190
	v_mad_i64_i32 v[130:131], s[20:21], v130, s62, v[128:129]
	v_lshl_add_u64 v[130:131], v[130:131], 0, s[4:5]
	v_lshl_add_u64 v[130:131], v[130:131], 0, s[8:9]
	v_lshl_add_u64 v[130:131], v[130:131], 0, v[176:177]
	v_cvt_pk_bf16_f32 v132, v108, v109
	v_cvt_pk_bf16_f32 v133, v110, v111
	v_cvt_pk_bf16_f32 v134, v104, v105
	v_cvt_pk_bf16_f32 v135, v106, v107
	s_nop 1
	v_permlane32_swap_b32_e32 v132, v134
	v_permlane32_swap_b32_e32 v133, v135
	global_store_dwordx4 v[130:131], v[132:135], off
	v_cvt_pk_bf16_f32 v136, v100, v101
	v_cvt_pk_bf16_f32 v137, v102, v103
	v_cvt_pk_bf16_f32 v138, v96, v97
	v_cvt_pk_bf16_f32 v139, v98, v99
	s_nop 1
	v_permlane32_swap_b32_e32 v136, v138
	v_permlane32_swap_b32_e32 v137, v139
	global_store_dwordx4 v[130:131], v[136:139], off offset:256
	v_add_u32_e32 v130, s28, v191
	v_mad_i64_i32 v[130:131], s[20:21], v130, s62, v[128:129]
	v_lshl_add_u64 v[130:131], v[130:131], 0, s[4:5]
	v_lshl_add_u64 v[130:131], v[130:131], 0, s[8:9]
	v_lshl_add_u64 v[130:131], v[130:131], 0, v[176:177]
	v_cvt_pk_bf16_f32 v132, v92, v93
	v_cvt_pk_bf16_f32 v133, v94, v95
	v_cvt_pk_bf16_f32 v134, v88, v89
	v_cvt_pk_bf16_f32 v135, v90, v91
	s_nop 1
	v_permlane32_swap_b32_e32 v132, v134
	v_permlane32_swap_b32_e32 v133, v135
	global_store_dwordx4 v[130:131], v[132:135], off
	v_cvt_pk_bf16_f32 v136, v84, v85
	v_cvt_pk_bf16_f32 v137, v86, v87
	v_cvt_pk_bf16_f32 v138, v80, v81
	v_cvt_pk_bf16_f32 v139, v82, v83
	s_nop 1
	v_permlane32_swap_b32_e32 v136, v138
	v_permlane32_swap_b32_e32 v137, v139
	global_store_dwordx4 v[130:131], v[136:139], off offset:256
	v_add_u32_e32 v130, s28, v192
	v_mad_i64_i32 v[130:131], s[20:21], v130, s62, v[128:129]
	v_lshl_add_u64 v[130:131], v[130:131], 0, s[4:5]
	v_lshl_add_u64 v[130:131], v[130:131], 0, s[8:9]
	v_lshl_add_u64 v[130:131], v[130:131], 0, v[176:177]
	v_cvt_pk_bf16_f32 v132, v76, v77
	v_cvt_pk_bf16_f32 v133, v78, v79
	v_cvt_pk_bf16_f32 v134, v72, v73
	v_cvt_pk_bf16_f32 v135, v74, v75
	s_nop 1
	v_permlane32_swap_b32_e32 v132, v134
	v_permlane32_swap_b32_e32 v133, v135
	global_store_dwordx4 v[130:131], v[132:135], off
	v_cvt_pk_bf16_f32 v136, v68, v69
	v_cvt_pk_bf16_f32 v137, v70, v71
	v_cvt_pk_bf16_f32 v138, v64, v65
	v_cvt_pk_bf16_f32 v139, v66, v67
	s_nop 1
	v_permlane32_swap_b32_e32 v136, v138
	v_permlane32_swap_b32_e32 v137, v139
	global_store_dwordx4 v[130:131], v[136:139], off offset:256
	v_add_u32_e32 v130, s28, v193
	v_mad_i64_i32 v[130:131], s[20:21], v130, s62, v[128:129]
	v_lshl_add_u64 v[130:131], v[130:131], 0, s[4:5]
	v_lshl_add_u64 v[130:131], v[130:131], 0, s[8:9]
	v_lshl_add_u64 v[130:131], v[130:131], 0, v[176:177]
	v_cvt_pk_bf16_f32 v132, v60, v61
	v_cvt_pk_bf16_f32 v133, v62, v63
	v_cvt_pk_bf16_f32 v134, v56, v57
	v_cvt_pk_bf16_f32 v135, v58, v59
	s_nop 1
	v_permlane32_swap_b32_e32 v132, v134
	v_permlane32_swap_b32_e32 v133, v135
	global_store_dwordx4 v[130:131], v[132:135], off
	v_cvt_pk_bf16_f32 v136, v52, v53
	v_cvt_pk_bf16_f32 v137, v54, v55
	v_cvt_pk_bf16_f32 v138, v48, v49
	v_cvt_pk_bf16_f32 v139, v50, v51
	s_nop 1
	v_permlane32_swap_b32_e32 v136, v138
	v_permlane32_swap_b32_e32 v137, v139
	global_store_dwordx4 v[130:131], v[136:139], off offset:256
	v_add_u32_e32 v130, s28, v194
	v_mad_i64_i32 v[130:131], s[20:21], v130, s62, v[128:129]
	v_lshl_add_u64 v[130:131], v[130:131], 0, s[4:5]
	v_lshl_add_u64 v[130:131], v[130:131], 0, s[8:9]
	v_lshl_add_u64 v[130:131], v[130:131], 0, v[176:177]
	v_cvt_pk_bf16_f32 v132, v44, v45
	v_cvt_pk_bf16_f32 v133, v46, v47
	v_cvt_pk_bf16_f32 v134, v40, v41
	v_cvt_pk_bf16_f32 v135, v42, v43
	s_nop 1
	v_permlane32_swap_b32_e32 v132, v134
	v_permlane32_swap_b32_e32 v133, v135
	global_store_dwordx4 v[130:131], v[132:135], off
	v_cvt_pk_bf16_f32 v136, v36, v37
	v_cvt_pk_bf16_f32 v137, v38, v39
	v_cvt_pk_bf16_f32 v138, v32, v33
	v_cvt_pk_bf16_f32 v139, v34, v35
	s_nop 1
	v_permlane32_swap_b32_e32 v136, v138
	v_permlane32_swap_b32_e32 v137, v139
	global_store_dwordx4 v[130:131], v[136:139], off offset:256
	v_add_u32_e32 v130, s28, v195
	v_mad_i64_i32 v[130:131], s[20:21], v130, s62, v[128:129]
	v_lshl_add_u64 v[130:131], v[130:131], 0, s[4:5]
	v_lshl_add_u64 v[130:131], v[130:131], 0, s[8:9]
	v_lshl_add_u64 v[130:131], v[130:131], 0, v[176:177]
	v_cvt_pk_bf16_f32 v132, v28, v29
	v_cvt_pk_bf16_f32 v133, v30, v31
	v_cvt_pk_bf16_f32 v134, v24, v25
	v_cvt_pk_bf16_f32 v135, v26, v27
	s_nop 1
	v_permlane32_swap_b32_e32 v132, v134
	v_permlane32_swap_b32_e32 v133, v135
	global_store_dwordx4 v[130:131], v[132:135], off
	v_cvt_pk_bf16_f32 v136, v20, v21
	v_cvt_pk_bf16_f32 v137, v22, v23
	v_cvt_pk_bf16_f32 v138, v16, v17
	v_cvt_pk_bf16_f32 v139, v18, v19
	s_nop 1
	v_permlane32_swap_b32_e32 v136, v138
	v_permlane32_swap_b32_e32 v137, v139
	global_store_dwordx4 v[130:131], v[136:139], off offset:256
	v_add_u32_e32 v130, s28, v196
	v_mad_i64_i32 v[128:129], s[20:21], v130, s62, v[128:129]
	v_lshl_add_u64 v[128:129], v[128:129], 0, s[4:5]
	v_lshl_add_u64 v[128:129], v[128:129], 0, s[8:9]
	v_lshl_add_u64 v[128:129], v[128:129], 0, v[176:177]
	v_cvt_pk_bf16_f32 v132, v12, v13
	v_cvt_pk_bf16_f32 v133, v14, v15
	v_cvt_pk_bf16_f32 v134, v8, v9
	v_cvt_pk_bf16_f32 v135, v10, v11
	s_nop 1
	v_permlane32_swap_b32_e32 v132, v134
	v_permlane32_swap_b32_e32 v133, v135
	global_store_dwordx4 v[128:129], v[132:135], off
	v_cvt_pk_bf16_f32 v136, v4, v5
	v_cvt_pk_bf16_f32 v137, v6, v7
	v_cvt_pk_bf16_f32 v138, v0, v1
	v_cvt_pk_bf16_f32 v139, v2, v3
	s_nop 1
	v_permlane32_swap_b32_e32 v136, v138
	v_permlane32_swap_b32_e32 v137, v139
	global_store_dwordx4 v[128:129], v[136:139], off offset:256
	s_cbranch_execnz .LBB0_610
